# LN sample rows on waves 0 and 2 of every workgroup instead of waves 0 and 1 (SIMD placement of the 9-row waves)
# baseline (speedup 1.0000x reference)
.LBB0_1219:
	s_or_b64 exec, exec, s[0:1]
	s_waitcnt lgkmcnt(0)
	v_mov_b32_e32 v0, v196
	v_readlane_b32 s8, v253, 27
	s_barrier
	v_readlane_b32 s9, v253, 28
	v_readlane_b32 s10, v253, 29
	v_readlane_b32 s11, v253, 30
	v_and_b32_e32 v49, 63, v0
	v_readfirstlane_b32 s3, v0
	v_mov_b32_e32 v0, s10
	v_mov_b32_e32 v1, s11
	v_readlane_b32 s6, v255, 0
	v_readlane_b32 s8, v255, 2
	v_mov_b32_e32 v48, s94
	v_mov_b32_e32 v50, s95
	v_lshlrev_b32_e32 v144, 4, v49
	v_readlane_b32 s7, v255, 1
	v_readlane_b32 s9, v255, 3
	v_readfirstlane_b32 s0, v0
	v_readfirstlane_b32 s1, v1
	s_nop 1
	global_load_dwordx4 v[0:3], v144, s[6:7]
	global_load_dwordx4 v[4:7], v144, s[6:7] offset:1024
	global_load_dwordx4 v[8:11], v144, s[8:9]
	global_load_dwordx4 v[12:15], v144, s[8:9] offset:1024
	global_load_dwordx4 v[16:19], v144, s[6:7] offset:2048
	global_load_dwordx4 v[20:23], v144, s[6:7] offset:3072
	global_load_dwordx4 v[24:27], v144, s[8:9] offset:2048
	global_load_dwordx4 v[28:31], v144, s[8:9] offset:3072
	s_ashr_i32 s3, s3, 6
	v_readlane_b32 s6, v253, 53
	s_add_i32 s10, s6, s3
	s_ashr_i32 s11, s10, 31
	s_lshr_b32 s18, s88, 1
	s_add_i32 s18, s18, s3
	s_lshr_b32 s18, s18, 1
	s_bitcmp1_b32 s3, 0
	s_cselect_b32 s18, 0x200, s18
	s_cmp_gt_u32 s3, 3
	s_cselect_b32 s18, 0x200, s18
	s_lshl_b64 s[6:7], s[10:11], 12
	s_add_u32 s6, s0, s6
	s_addc_u32 s7, s1, s7
	v_lshl_add_u64 v[32:33], s[6:7], 0, v[144:145]
	s_mov_b32 s3, 0x100000
	global_load_dwordx4 v[108:111], v144, s[6:7]
	global_load_dwordx4 v[104:107], v144, s[6:7] offset:1024
	global_load_dwordx4 v[100:103], v144, s[6:7] offset:2048
	global_load_dwordx4 v[88:91], v144, s[6:7] offset:3072
	s_mov_b64 s[6:7], 0x100000
	v_add_co_u32_e32 v36, vcc, s3, v32
	v_lshl_add_u64 v[44:45], v[32:33], 0, s[6:7]
	s_nop 0
	v_addc_co_u32_e32 v37, vcc, 0, v33, vcc
	global_load_dwordx4 v[32:35], v[44:45], off offset:1024
	global_load_dwordx4 v[40:43], v[44:45], off offset:2048
	s_nop 0
	global_load_dwordx4 v[36:39], v[36:37], off
	s_nop 0
	global_load_dwordx4 v[44:47], v[44:45], off offset:3072
	s_cmpk_lt_i32 s18, 0x200
	v_readfirstlane_b32 s8, v48
	s_cselect_b32 s11, 9, 8
	s_addk_i32 s18, 0x4000
	v_and_b32_e32 v53, 64, v220
	v_readfirstlane_b32 s9, v50
	s_add_u32 s19, s8, 0x306000
	v_xor_b32_e32 v51, 16, v220
	v_add_u32_e32 v53, 64, v53
	s_addc_u32 s20, s9, 0
	v_cmp_lt_i32_e32 vcc, v51, v53
	s_add_u32 s21, s8, 0x10800000
	s_addc_u32 s22, s9, 0
	v_cndmask_b32_e32 v51, v220, v51, vcc
	v_lshlrev_b32_e32 v151, 2, v51
	v_xor_b32_e32 v51, 32, v220
	v_lshlrev_b32_e32 v48, 2, v49
	v_cmp_lt_i32_e32 vcc, v51, v53
	s_add_u32 s23, s8, 0x280000
	v_lshl_add_u64 v[154:155], s[0:1], 0, v[144:145]
	v_lshlrev_b32_e32 v144, 3, v49
	v_or_b32_e32 v50, 0x100, v48
	v_or_b32_e32 v52, 0x200, v48
	v_or_b32_e32 v54, 0x300, v48
	v_cndmask_b32_e32 v51, v220, v51, vcc
	s_addc_u32 s24, s9, 0
	v_lshl_add_u64 v[56:57], s[8:9], 0, v[144:145]
	s_mov_b64 s[8:9], 0x6300000
	s_mov_b32 s3, 0
	v_lshlrev_b32_e32 v158, 2, v51
	v_cmp_eq_u32_e64 s[6:7], 0, v49
	v_lshl_add_u64 v[156:157], v[56:57], 0, s[8:9]
	v_lshlrev_b32_e32 v144, 2, v48
	v_lshlrev_b32_e32 v159, 2, v50
	v_lshlrev_b32_e32 v160, 2, v52
	v_lshlrev_b32_e32 v161, 2, v54
	s_waitcnt vmcnt(0)
	s_branch .LBB0_1221

.LBB0_1434:
	s_or_b64 exec, exec, s[6:7]
	s_mov_b64 s[6:7], -1
	s_and_b64 vcc, exec, s[0:1]
	s_waitcnt lgkmcnt(0)
	s_barrier
	s_cbranch_vccz .LBB0_1467
	v_mov_b32_e32 v0, v196
	v_readlane_b32 s8, v253, 27
	v_readlane_b32 s10, v253, 29
	v_readlane_b32 s11, v253, 30
	v_and_b32_e32 v37, 63, v0
	v_readfirstlane_b32 s6, v0
	v_mov_b32_e32 v0, s10
	v_mov_b32_e32 v1, s11
	v_readlane_b32 s9, v253, 28
	v_readfirstlane_b32 s12, v0
	v_readfirstlane_b32 s13, v1
	v_mov_b32_e32 v0, s94
	v_mov_b32_e32 v1, s95
	v_readlane_b32 s10, v255, 7
	v_readfirstlane_b32 s8, v0
	v_readfirstlane_b32 s9, v1
	s_add_u32 s3, s8, 0x300000
	v_readlane_b32 s14, v255, 11
	s_addc_u32 s20, s9, 0
	v_lshlrev_b32_e32 v144, 4, v37
	v_readlane_b32 s11, v255, 8
	v_readlane_b32 s15, v255, 12
	s_ashr_i32 s6, s6, 6
	v_readlane_b32 s7, v253, 53
	s_nop 1
	global_load_dwordx4 v[0:3], v144, s[10:11]
	global_load_dwordx4 v[4:7], v144, s[10:11] offset:1024
	global_load_dwordx4 v[8:11], v144, s[14:15]
	global_load_dwordx4 v[12:15], v144, s[14:15] offset:1024
	global_load_dwordx4 v[16:19], v144, s[10:11] offset:2048
	global_load_dwordx4 v[20:23], v144, s[10:11] offset:3072
	global_load_dwordx4 v[24:27], v144, s[14:15] offset:2048
	global_load_dwordx4 v[28:31], v144, s[14:15] offset:3072
	s_add_i32 s14, s7, s6
	s_ashr_i32 s15, s14, 31
	s_lshr_b32 s24, s88, 1
	s_add_i32 s24, s24, s6
	s_lshr_b32 s24, s24, 1
	s_bitcmp1_b32 s6, 0
	s_cselect_b32 s24, 0x200, s24
	s_cmp_gt_u32 s6, 3
	s_cselect_b32 s24, 0x200, s24
	s_lshl_b64 s[6:7], s[14:15], 12
	s_add_u32 s6, s12, s6
	s_addc_u32 s7, s13, s7
	v_lshl_add_u64 v[32:33], s[6:7], 0, v[144:145]
	global_load_dwordx4 v[100:103], v144, s[6:7]
	global_load_dwordx4 v[104:107], v144, s[6:7] offset:1024
	global_load_dwordx4 v[108:111], v144, s[6:7] offset:2048
	global_load_dwordx4 v[96:99], v144, s[6:7] offset:3072
	s_mov_b64 s[6:7], 0x100000
	v_lshl_add_u64 v[34:35], v[32:33], 0, s[6:7]
	s_mov_b32 s6, 0x100000
	v_add_co_u32_e32 v32, vcc, s6, v32
	s_add_u32 s15, s8, 0x6300000
	s_nop 0
	v_addc_co_u32_e32 v33, vcc, 0, v33, vcc
	global_load_dwordx4 v[84:87], v[34:35], off offset:1024
	global_load_dwordx4 v[88:91], v[34:35], off offset:2048
	global_load_dwordx4 v[80:83], v[32:33], off
	global_load_dwordx4 v[92:95], v[34:35], off offset:3072
	v_and_b32_e32 v35, 64, v220
	v_xor_b32_e32 v33, 16, v220
	v_add_u32_e32 v35, 64, v35
	s_addc_u32 s21, s9, 0
	v_cmp_lt_i32_e32 vcc, v33, v35
	s_cmpk_lt_i32 s24, 0x200
	s_cselect_b32 s23, 9, 8
	v_cndmask_b32_e32 v33, v220, v33, vcc
	s_addk_i32 s24, 0x4000
	v_lshlrev_b32_e32 v121, 2, v33
	v_xor_b32_e32 v33, 32, v220
	v_lshlrev_b32_e32 v120, 2, v37
	v_cmp_lt_i32_e32 vcc, v33, v35
	s_add_u32 s25, s8, 0x280000
	v_or_b32_e32 v32, 0x100, v120
	v_or_b32_e32 v34, 0x200, v120
	v_or_b32_e32 v36, 0x300, v120
	v_cndmask_b32_e32 v33, v220, v33, vcc
	s_addc_u32 s26, s9, 0
	v_lshl_add_u64 v[38:39], s[8:9], 0, v[144:145]
	s_mov_b64 s[8:9], 0x10800000
	s_mov_b32 s22, 0
	v_lshlrev_b32_e32 v128, 2, v33
	v_cmp_eq_u32_e64 s[6:7], 0, v37
	v_lshl_add_u64 v[122:123], s[12:13], 0, v[144:145]
	v_lshl_add_u64 v[124:125], v[38:39], 0, s[8:9]
	v_lshlrev_b32_e32 v129, 2, v32
	v_lshlrev_b32_e32 v130, 2, v34
	v_lshlrev_b32_e32 v131, 2, v36
	s_waitcnt vmcnt(0)
	s_branch .LBB0_1437

.LBB0_1467:
	s_and_b64 vcc, exec, s[6:7]
	s_cbranch_vccz .LBB0_1489
	v_mov_b32_e32 v0, v196
	v_readlane_b32 s8, v253, 27
	v_readlane_b32 s9, v253, 28
	v_readlane_b32 s10, v253, 29
	v_readlane_b32 s11, v253, 30
	v_and_b32_e32 v49, 63, v0
	v_readfirstlane_b32 s3, v0
	v_mov_b32_e32 v0, s10
	v_mov_b32_e32 v1, s11
	v_readlane_b32 s6, v255, 5
	v_readlane_b32 s8, v255, 9
	v_mov_b32_e32 v48, s94
	v_mov_b32_e32 v50, s95
	v_lshlrev_b32_e32 v144, 4, v49
	v_readlane_b32 s7, v255, 6
	v_readlane_b32 s9, v255, 10
	v_readfirstlane_b32 s10, v0
	v_readfirstlane_b32 s11, v1
	s_nop 1
	global_load_dwordx4 v[0:3], v144, s[6:7]
	global_load_dwordx4 v[4:7], v144, s[6:7] offset:1024
	global_load_dwordx4 v[8:11], v144, s[8:9]
	global_load_dwordx4 v[12:15], v144, s[8:9] offset:1024
	global_load_dwordx4 v[16:19], v144, s[6:7] offset:2048
	global_load_dwordx4 v[20:23], v144, s[6:7] offset:3072
	global_load_dwordx4 v[24:27], v144, s[8:9] offset:2048
	global_load_dwordx4 v[28:31], v144, s[8:9] offset:3072
	s_ashr_i32 s3, s3, 6
	v_readlane_b32 s6, v253, 53
	s_add_i32 s12, s6, s3
	s_ashr_i32 s13, s12, 31
	s_lshr_b32 s20, s88, 1
	s_add_i32 s20, s20, s3
	s_lshr_b32 s20, s20, 1
	s_bitcmp1_b32 s3, 0
	s_cselect_b32 s20, 0x200, s20
	s_cmp_gt_u32 s3, 3
	s_cselect_b32 s20, 0x200, s20
	s_lshl_b64 s[6:7], s[12:13], 12
	s_add_u32 s6, s10, s6
	s_addc_u32 s7, s11, s7
	s_waitcnt vmcnt(13)
	v_lshl_add_u64 v[32:33], s[6:7], 0, v[144:145]
	s_mov_b32 s3, 0x100000
	global_load_dwordx4 v[100:103], v144, s[6:7]
	global_load_dwordx4 v[104:107], v144, s[6:7] offset:1024
	global_load_dwordx4 v[108:111], v144, s[6:7] offset:2048
	global_load_dwordx4 v[88:91], v144, s[6:7] offset:3072
	s_mov_b64 s[6:7], 0x100000
	s_waitcnt vmcnt(15)
	v_add_co_u32_e32 v36, vcc, s3, v32
	v_lshl_add_u64 v[44:45], v[32:33], 0, s[6:7]
	s_nop 0
	v_addc_co_u32_e32 v37, vcc, 0, v33, vcc
	global_load_dwordx4 v[32:35], v[44:45], off offset:1024
	global_load_dwordx4 v[40:43], v[44:45], off offset:2048
	s_nop 0
	global_load_dwordx4 v[36:39], v[36:37], off
	s_nop 0
	global_load_dwordx4 v[44:47], v[44:45], off offset:3072
	v_and_b32_e32 v53, 64, v220
	s_cmpk_lt_i32 s20, 0x200
	v_xor_b32_e32 v51, 16, v220
	v_add_u32_e32 v53, 64, v53
	v_readfirstlane_b32 s8, v48
	s_cselect_b32 s13, 9, 8
	s_addk_i32 s20, 0x4000
	v_cmp_lt_i32_e32 vcc, v51, v53
	v_readfirstlane_b32 s9, v50
	s_add_u32 s21, s8, 0x303000
	v_cndmask_b32_e32 v51, v220, v51, vcc
	s_addc_u32 s22, s9, 0
	v_lshlrev_b32_e32 v128, 2, v51
	v_xor_b32_e32 v51, 32, v220
	v_lshlrev_b32_e32 v56, 3, v49
	v_mov_b32_e32 v57, v145
	v_lshlrev_b32_e32 v48, 2, v49
	v_cmp_lt_i32_e32 vcc, v51, v53
	s_add_u32 s23, s8, 0x280000
	v_lshl_add_u64 v[56:57], s[8:9], 0, v[56:57]
	s_mov_b64 s[14:15], 0x6300000
	v_or_b32_e32 v50, 0x100, v48
	v_or_b32_e32 v52, 0x200, v48
	v_or_b32_e32 v54, 0x300, v48
	v_cndmask_b32_e32 v51, v220, v51, vcc
	s_addc_u32 s24, s9, 0
	v_lshl_add_u64 v[122:123], v[56:57], 0, s[14:15]
	v_lshl_add_u64 v[56:57], s[8:9], 0, v[144:145]
	s_mov_b64 s[8:9], 0x10800000
	s_mov_b32 s3, 0
	v_lshlrev_b32_e32 v129, 2, v51
	v_cmp_eq_u32_e64 s[6:7], 0, v49
	v_lshl_add_u64 v[120:121], s[10:11], 0, v[144:145]
	v_lshl_add_u64 v[124:125], v[56:57], 0, s[8:9]
	v_lshlrev_b32_e32 v130, 2, v48
	v_lshlrev_b32_e32 v131, 2, v50
	v_lshlrev_b32_e32 v132, 2, v52
	v_lshlrev_b32_e32 v133, 2, v54
	s_waitcnt vmcnt(0)
	s_branch .LBB0_1470
